# R7_CA: S0 loads issued together, running sum batched, S2 loads hoisted above the running sum, LDS reads batched, 8-lane sums via DPP; ML_SCAN gate block before commit
# speedup vs baseline: 1.0402x; 1.0402x over previous
; __device__ __forceinline__ float sigm(float x) { return __builtin_amdgcn_rcpf(1.f + __expf(-x)); }
; __device__ __forceinline__ void ph_r7_ca(const P& p, int j, int win, char* smem) {
;     ...
;     const int chain = it / 20, cl = it - chain * 20, c = c0 + cl, d = chain & 1, b = chain >> 5, h = (chain >> 1) & 15;
;     {
;       const int rowA = rowmap(d, b, 64 * c + 16 * ti + l15);
;       const float* w0 = p.r7_w0 + (size_t)(j * 2 + d) * 1024 + h * 64; const float* a0 = p.r7_a0 + (size_t)(j * 2 + d) * 1024 + h * 64;
; #pragma unroll
;       for (int tt = 0; tt < 2; tt++) { const int tj = tj0 + tt; f32x4 aw = f32x4{0.f, 0.f, 0.f, 0.f}, aa = aw;
; #pragma unroll
;         for (int ks = 0; ks < 2; ks++) {
;           bf16x8 xw = *(const bf16x8*)(WMb + (size_t)rowA * 128 + d * 64 + 32 * ks + 8 * q4), xa = *(const bf16x8*)(AMb + (size_t)rowA * 128 + d * 64 + 32 * ks + 8 * q4);
;           bf16x8 yw = *(const bf16x8*)(p.W + WR_UP + d * 65536 + (size_t)(h * 64 + 16 * tj + l15) * 64 + 32 * ks + 8 * q4);
;           bf16x8 ya = *(const bf16x8*)(p.W + WR_UP + (2 + d) * 65536 + (size_t)(h * 64 + 16 * tj + l15) * 64 + 32 * ks + 8 * q4);
;           aw = __builtin_amdgcn_mfma_f32_16x16x32_bf16(xw, yw, aw, 0, 0, 0); aa = __builtin_amdgcn_mfma_f32_16x16x32_bf16(xa, ya, aa, 0, 0, 0); }
;         const int ch = 16 * tj + l15; const float w0v = w0[ch], a0v = a0[ch];
; #pragma unroll
;         for (int jj = 0; jj < 4; jj++) { const int tau = 16 * ti + 4 * q4 + jj; LW[tau * 64 + ch] = -0.6065306597126334f * sigm(w0v + aw[jj]); AT[tau * 64 + ch] = sigm(a0v + aa[jj]); }
;       }
.LBB0_187:
	s_mul_hi_i32 s28, s84, 0x66666667
	s_lshr_b32 s30, s28, 31
	s_ashr_i32 s28, s28, 3
	s_add_i32 s28, s28, s30
	s_sub_i32 s30, s18, s28
	s_mul_i32 s30, s30, 20
	s_add_i32 s30, s30, s84
	s_and_b32 s86, s28, 1
	s_lshr_b32 s90, s28, 5
	s_bfe_u32 s85, s28, 0x40001
	s_lshl_b32 s87, s30, 6
	s_cmp_eq_u32 s86, 0
	s_cselect_b64 vcc, -1, 0
	s_or_b32 s30, s86, s19
	s_ashr_i32 s31, s30, 31
	v_readlane_b32 s8, v253, 41
	s_lshl_b64 s[30:31], s[30:31], 12
	v_readlane_b32 s10, v253, 43
	v_add_u32_e32 v0, s87, v54
	v_readlane_b32 s11, v253, 44
	s_add_u32 s28, s10, s30
	v_cmp_lt_i32_e64 s[88:89], s15, v0
	s_addc_u32 s40, s11, s31
	s_lshl_b32 s91, s85, 6
	s_lshl_b32 s41, s85, 8
	v_cndmask_b32_e64 v2, v176, v177, s[88:89]
	v_readlane_b32 s9, v253, 42
	s_add_u32 s88, s28, s41
	v_sub_u32_e32 v2, v2, v0
	s_addc_u32 s89, s40, 0
	v_readlane_b32 s8, v253, 45
	v_cndmask_b32_e32 v0, v2, v0, vcc
	s_mulk_i32 s90, 0x4100
	v_readlane_b32 s9, v253, 46
	s_add_u32 s28, s8, s30
	v_add_u32_e32 v2, s90, v0
	s_addc_u32 s31, s9, s31
	s_add_u32 s30, s28, s41
	v_ashrrev_i32_e32 v3, 31, v2
	v_readlane_b32 s40, v251, 23
	v_lshlrev_b64 v[2:3], 8, v[2:3]
	v_readlane_b32 s41, v251, 24
	s_addc_u32 s31, s31, 0
	v_lshl_add_u64 v[4:5], s[36:37], 0, v[2:3]
	s_lshl_b32 s28, s86, 7
	v_lshl_add_u64 v[2:3], s[40:41], 0, v[2:3]
	v_lshl_add_u64 v[4:5], v[4:5], 0, s[28:29]
	v_lshl_add_u64 v[2:3], v[2:3], 0, s[28:29]
	s_lshl_b32 s28, s86, 17
	v_readlane_b32 s40, v251, 27
	s_add_u32 s40, s40, s28
	v_readlane_b32 s28, v251, 28
	v_mov_b32_e32 v41, v1
	s_addc_u32 s41, s28, 0
	v_or_b32_e32 v0, s91, v37
	v_lshl_add_u64 v[30:31], v[4:5], 0, v[40:41]
	v_lshl_add_u64 v[46:47], v[2:3], 0, v[40:41]
	v_lshl_add_u64 v[18:19], s[40:41], 0, v[40:41]
	v_lshlrev_b32_e32 v41, 6, v0
	s_mov_b64 s[40:41], 0x40000
	v_or_b32_e32 v0, v41, v71
	v_lshl_add_u64 v[20:21], v[18:19], 0, s[40:41]
	v_lshlrev_b32_e32 v0, 1, v0
	v_lshl_add_u64 v[48:49], v[18:19], 0, v[0:1]
	v_lshl_add_u64 v[50:51], v[20:21], 0, v[0:1]
	v_or_b32_e32 v0, v41, v77
	v_lshlrev_b32_e32 v0, 1, v0
	v_lshl_add_u64 v[26:27], v[18:19], 0, v[0:1]
	v_lshl_add_u64 v[28:29], v[20:21], 0, v[0:1]
	global_load_dwordx4 v[2:5], v[30:31], off
	global_load_dwordx4 v[6:9], v[46:47], off
	global_load_dwordx4 v[212:215], v[48:49], off
	global_load_dwordx4 v[216:219], v[50:51], off
	global_load_dwordx4 v[10:13], v[30:31], off offset:64
	global_load_dwordx4 v[14:17], v[46:47], off offset:64
	global_load_dwordx4 v[220:223], v[48:49], off offset:64
	global_load_dwordx4 v[224:227], v[50:51], off offset:64
	global_load_dwordx4 v[228:231], v[26:27], off
	global_load_dwordx4 v[232:235], v[28:29], off
	global_load_dwordx4 v[236:239], v[26:27], off offset:64
	global_load_dwordx4 v[240:243], v[28:29], off offset:64
	global_load_dword v244, v208, s[88:89]
	global_load_dword v245, v208, s[30:31]
	global_load_dword v246, v209, s[88:89]
	global_load_dword v247, v209, s[30:31]
	v_readlane_b32 s8, v254, 61
	v_readlane_b32 s9, v254, 62
	v_readlane_b32 s10, v253, 47
	v_readlane_b32 s11, v253, 48
	s_waitcnt vmcnt(12)
	v_mfma_f32_16x16x32_bf16 v[22:25], v[2:5], v[212:215], 0
	v_mfma_f32_16x16x32_bf16 v[26:29], v[6:9], v[216:219], 0
	s_waitcnt vmcnt(8)
	v_mfma_f32_16x16x32_bf16 v[22:25], v[10:13], v[220:223], v[22:25]
	v_mfma_f32_16x16x32_bf16 v[26:29], v[14:17], v[224:227], v[26:29]
	s_waitcnt vmcnt(6)
	v_mfma_f32_16x16x32_bf16 v[18:21], v[2:5], v[228:231], 0
	v_mfma_f32_16x16x32_bf16 v[46:49], v[6:9], v[232:235], 0
	s_waitcnt vmcnt(4)
	v_mfma_f32_16x16x32_bf16 v[18:21], v[10:13], v[236:239], v[18:21]
	v_mfma_f32_16x16x32_bf16 v[46:49], v[14:17], v[240:243], v[46:49]
	s_waitcnt vmcnt(0)
	s_nop 3
	v_add_f32_e32 v22, v22, v244
	v_add_f32_e32 v23, v23, v244
	v_add_f32_e32 v24, v24, v244
	v_add_f32_e32 v25, v25, v244
	v_mul_f32_e32 v22, 0xbfb8aa3b, v22
	v_mul_f32_e32 v23, 0xbfb8aa3b, v23
	v_mul_f32_e32 v24, 0xbfb8aa3b, v24
	v_mul_f32_e32 v25, 0xbfb8aa3b, v25
	v_exp_f32_e32 v22, v22
	v_exp_f32_e32 v23, v23
	v_exp_f32_e32 v24, v24
	v_exp_f32_e32 v25, v25
	v_add_f32_e32 v22, 1.0, v22
	v_add_f32_e32 v23, 1.0, v23
	v_add_f32_e32 v24, 1.0, v24
	v_add_f32_e32 v25, 1.0, v25
	v_rcp_f32_e32 v22, v22
	v_rcp_f32_e32 v23, v23
	v_rcp_f32_e32 v24, v24
	v_rcp_f32_e32 v25, v25
	v_mul_f32_e32 v22, 0xbf1b4598, v22
	v_mul_f32_e32 v23, 0xbf1b4598, v23
	v_mul_f32_e32 v24, 0xbf1b4598, v24
	v_mul_f32_e32 v25, 0xbf1b4598, v25
	v_add_f32_e32 v26, v26, v245
	v_add_f32_e32 v27, v27, v245
	v_add_f32_e32 v28, v28, v245
	v_add_f32_e32 v29, v29, v245
	v_mul_f32_e32 v26, 0xbfb8aa3b, v26
	v_mul_f32_e32 v27, 0xbfb8aa3b, v27
	v_mul_f32_e32 v28, 0xbfb8aa3b, v28
	v_mul_f32_e32 v29, 0xbfb8aa3b, v29
	v_exp_f32_e32 v26, v26
	v_exp_f32_e32 v27, v27
	v_exp_f32_e32 v28, v28
	v_exp_f32_e32 v29, v29
	v_add_f32_e32 v26, 1.0, v26
	v_add_f32_e32 v27, 1.0, v27
	v_add_f32_e32 v28, 1.0, v28
	v_add_f32_e32 v29, 1.0, v29
	v_rcp_f32_e32 v26, v26
	v_rcp_f32_e32 v27, v27
	v_rcp_f32_e32 v28, v28
	v_rcp_f32_e32 v29, v29
	ds_write_b32 v73, v26
	ds_write2st64_b32 v72, v22, v23 offset0:252 offset1:253
	ds_write_b32 v74, v27
	ds_write_b32 v72, v24 offset:65024
	ds_write_b32 v75, v28
	ds_write_b32 v72, v25 offset:65280
	ds_write_b32 v76, v29
	v_add_f32_e32 v18, v18, v246
	v_add_f32_e32 v19, v19, v246
	v_add_f32_e32 v20, v20, v246
	v_add_f32_e32 v21, v21, v246
	v_mul_f32_e32 v18, 0xbfb8aa3b, v18
	v_mul_f32_e32 v19, 0xbfb8aa3b, v19
	v_mul_f32_e32 v20, 0xbfb8aa3b, v20
	v_mul_f32_e32 v21, 0xbfb8aa3b, v21
	v_exp_f32_e32 v18, v18
	v_exp_f32_e32 v19, v19
	v_exp_f32_e32 v20, v20
	v_exp_f32_e32 v21, v21
	v_add_f32_e32 v18, 1.0, v18
	v_add_f32_e32 v19, 1.0, v19
	v_add_f32_e32 v20, 1.0, v20
	v_add_f32_e32 v21, 1.0, v21
	v_rcp_f32_e32 v18, v18
	v_rcp_f32_e32 v19, v19
	v_rcp_f32_e32 v20, v20
	v_rcp_f32_e32 v21, v21
	v_mul_f32_e32 v18, 0xbf1b4598, v18
	v_mul_f32_e32 v19, 0xbf1b4598, v19
	v_mul_f32_e32 v20, 0xbf1b4598, v20
	v_mul_f32_e32 v21, 0xbf1b4598, v21
	v_add_f32_e32 v46, v46, v247
	v_add_f32_e32 v47, v47, v247
	v_add_f32_e32 v48, v48, v247
	v_add_f32_e32 v49, v49, v247
	v_mul_f32_e32 v46, 0xbfb8aa3b, v46
	v_mul_f32_e32 v47, 0xbfb8aa3b, v47
	v_mul_f32_e32 v48, 0xbfb8aa3b, v48
	v_mul_f32_e32 v49, 0xbfb8aa3b, v49
	v_exp_f32_e32 v46, v46
	v_exp_f32_e32 v47, v47
	v_exp_f32_e32 v48, v48
	v_exp_f32_e32 v49, v49
	v_add_f32_e32 v46, 1.0, v46
	v_add_f32_e32 v47, 1.0, v47
	v_add_f32_e32 v48, 1.0, v48
	v_add_f32_e32 v49, 1.0, v49
	v_rcp_f32_e32 v46, v46
	v_rcp_f32_e32 v47, v47
	v_rcp_f32_e32 v48, v48
	v_rcp_f32_e32 v49, v49
	ds_write_b32 v79, v46
	ds_write2st64_b32 v78, v18, v19 offset0:252 offset1:253
	ds_write_b32 v80, v47
	ds_write_b32 v78, v20 offset:65024
	ds_write_b32 v81, v48
	ds_write_b32 v78, v21 offset:65280
	ds_write_b32 v82, v49
	s_waitcnt lgkmcnt(0)
	s_barrier
; __device__ __forceinline__ float blo(unsigned u) { return __uint_as_float(u << 16); }
; __device__ __forceinline__ float bhi(unsigned u) { return __uint_as_float(u & 0xffff0000u); }
; __device__ __forceinline__ void ph_r7_ca(const P& p, int j, int win, char* smem) {
;     ...
;     if (tid < 64) { float acc = 0.f;
; #pragma unroll 8
;       for (int t = 0; t < 64; t++) { acc += LW[t * 64 + tid]; LW[t * 64 + tid] = acc; } }
;     __syncthreads();
;     {
;       const int tau = tid >> 3, sc = tid & 7, col = h * 64 + sc * 8; const int row = rowmap(d, b, 64 * c + tau);
;       const bfr* rp = RK + (size_t)row * 4096 + col; uint4 pr = *(const uint4*)rp, pk = *(const uint4*)(rp + 1024);
;       unsigned ur[4] = {pr.x, pr.y, pr.z, pr.w}, uk[4] = {pk.x, pk.y, pk.z, pk.w};
;       float r8[8], k8[8], kr[8];
; #pragma unroll
;       for (int e = 0; e < 4; e++) { r8[2 * e] = blo(ur[e]); r8[2 * e + 1] = bhi(ur[e]); k8[2 * e] = blo(uk[e]); k8[2 * e + 1] = bhi(uk[e]); }
;       float ss = 0.f;
; #pragma unroll
;       for (int e = 0; e < 8; e++) { kr[e] = k8[e] * kkp[col + e]; ss += kr[e] * kr[e]; }
	v_add_u32_e32 v0, s87, v52
	v_cmp_lt_i32_e64 s[88:89], s15, v0
	v_or_b32_e32 v12, s91, v56
	s_nop 0
	v_cndmask_b32_e64 v2, v176, v177, s[88:89]
	v_sub_u32_e32 v2, v2, v0
	v_cndmask_b32_e32 v0, v2, v0, vcc
	v_add_u32_e32 v6, s90, v0
	v_ashrrev_i32_e32 v7, 31, v6
	v_lshlrev_b64 v[2:3], 13, v[6:7]
	v_lshl_add_u64 v[2:3], s[38:39], 0, v[2:3]
	v_lshlrev_b32_e32 v0, 1, v12
	v_lshl_add_u64 v[8:9], v[2:3], 0, v[0:1]
	v_lshlrev_b32_e32 v0, 2, v12
	global_load_dwordx4 v[2:5], v[8:9], off
	global_load_dwordx4 v[8:11], v[8:9], off offset:2048
	global_load_dwordx4 v[244:247], v0, s[92:93] offset:16
	global_load_dwordx4 v[14:17], v0, s[92:93]
	s_and_saveexec_b64 s[30:31], s[8:9]
	s_cbranch_execz .LBB0_190
	v_add_u32_e32 v26, 0xfc00, v55
	v_mov_b32_e32 v27, 0
	ds_read2st64_b32 v[212:213], v26 offset0:0 offset1:1
	ds_read2st64_b32 v[214:215], v26 offset0:2 offset1:3
	ds_read2st64_b32 v[216:217], v26 offset0:4 offset1:5
	ds_read2st64_b32 v[218:219], v26 offset0:6 offset1:7
	ds_read2st64_b32 v[220:221], v26 offset0:8 offset1:9
	ds_read2st64_b32 v[222:223], v26 offset0:10 offset1:11
	ds_read2st64_b32 v[224:225], v26 offset0:12 offset1:13
	ds_read2st64_b32 v[226:227], v26 offset0:14 offset1:15
	ds_read2st64_b32 v[228:229], v26 offset0:16 offset1:17
	ds_read2st64_b32 v[230:231], v26 offset0:18 offset1:19
	ds_read2st64_b32 v[232:233], v26 offset0:20 offset1:21
	ds_read2st64_b32 v[234:235], v26 offset0:22 offset1:23
	ds_read2st64_b32 v[236:237], v26 offset0:24 offset1:25
	ds_read2st64_b32 v[238:239], v26 offset0:26 offset1:27
	ds_read2st64_b32 v[240:241], v26 offset0:28 offset1:29
	ds_read2st64_b32 v[242:243], v26 offset0:30 offset1:31
	s_waitcnt lgkmcnt(8)
	v_add_f32_e32 v212, v27, v212
	v_add_f32_e32 v213, v212, v213
	v_add_f32_e32 v214, v213, v214
	v_add_f32_e32 v215, v214, v215
	v_add_f32_e32 v216, v215, v216
	v_add_f32_e32 v217, v216, v217
	v_add_f32_e32 v218, v217, v218
	v_add_f32_e32 v219, v218, v219
	v_add_f32_e32 v220, v219, v220
	v_add_f32_e32 v221, v220, v221
	v_add_f32_e32 v222, v221, v222
	v_add_f32_e32 v223, v222, v223
	v_add_f32_e32 v224, v223, v224
	v_add_f32_e32 v225, v224, v225
	v_add_f32_e32 v226, v225, v226
	v_add_f32_e32 v227, v226, v227
	v_mov_b32_e32 v27, v227
	ds_write2st64_b32 v26, v212, v213 offset0:0 offset1:1
	ds_write2st64_b32 v26, v214, v215 offset0:2 offset1:3
	ds_write2st64_b32 v26, v216, v217 offset0:4 offset1:5
	ds_write2st64_b32 v26, v218, v219 offset0:6 offset1:7
	ds_write2st64_b32 v26, v220, v221 offset0:8 offset1:9
	ds_write2st64_b32 v26, v222, v223 offset0:10 offset1:11
	ds_write2st64_b32 v26, v224, v225 offset0:12 offset1:13
	ds_write2st64_b32 v26, v226, v227 offset0:14 offset1:15
	s_waitcnt lgkmcnt(8)
	ds_read2st64_b32 v[212:213], v26 offset0:32 offset1:33
	ds_read2st64_b32 v[214:215], v26 offset0:34 offset1:35
	ds_read2st64_b32 v[216:217], v26 offset0:36 offset1:37
	ds_read2st64_b32 v[218:219], v26 offset0:38 offset1:39
	ds_read2st64_b32 v[220:221], v26 offset0:40 offset1:41
	ds_read2st64_b32 v[222:223], v26 offset0:42 offset1:43
	ds_read2st64_b32 v[224:225], v26 offset0:44 offset1:45
	ds_read2st64_b32 v[226:227], v26 offset0:46 offset1:47
	v_add_f32_e32 v228, v27, v228
	v_add_f32_e32 v229, v228, v229
	v_add_f32_e32 v230, v229, v230
	v_add_f32_e32 v231, v230, v231
	v_add_f32_e32 v232, v231, v232
	v_add_f32_e32 v233, v232, v233
	v_add_f32_e32 v234, v233, v234
	v_add_f32_e32 v235, v234, v235
	v_add_f32_e32 v236, v235, v236
	v_add_f32_e32 v237, v236, v237
	v_add_f32_e32 v238, v237, v238
	v_add_f32_e32 v239, v238, v239
	v_add_f32_e32 v240, v239, v240
	v_add_f32_e32 v241, v240, v241
	v_add_f32_e32 v242, v241, v242
	v_add_f32_e32 v243, v242, v243
	v_mov_b32_e32 v27, v243
	ds_write2st64_b32 v26, v228, v229 offset0:16 offset1:17
	ds_write2st64_b32 v26, v230, v231 offset0:18 offset1:19
	ds_write2st64_b32 v26, v232, v233 offset0:20 offset1:21
	ds_write2st64_b32 v26, v234, v235 offset0:22 offset1:23
	ds_write2st64_b32 v26, v236, v237 offset0:24 offset1:25
	ds_write2st64_b32 v26, v238, v239 offset0:26 offset1:27
	ds_write2st64_b32 v26, v240, v241 offset0:28 offset1:29
	ds_write2st64_b32 v26, v242, v243 offset0:30 offset1:31
	s_waitcnt lgkmcnt(8)
	ds_read2st64_b32 v[228:229], v26 offset0:48 offset1:49
	ds_read2st64_b32 v[230:231], v26 offset0:50 offset1:51
	ds_read2st64_b32 v[232:233], v26 offset0:52 offset1:53
	ds_read2st64_b32 v[234:235], v26 offset0:54 offset1:55
	ds_read2st64_b32 v[236:237], v26 offset0:56 offset1:57
	ds_read2st64_b32 v[238:239], v26 offset0:58 offset1:59
	ds_read2st64_b32 v[240:241], v26 offset0:60 offset1:61
	ds_read2st64_b32 v[242:243], v26 offset0:62 offset1:63
	v_add_f32_e32 v212, v27, v212
	v_add_f32_e32 v213, v212, v213
	v_add_f32_e32 v214, v213, v214
	v_add_f32_e32 v215, v214, v215
	v_add_f32_e32 v216, v215, v216
	v_add_f32_e32 v217, v216, v217
	v_add_f32_e32 v218, v217, v218
	v_add_f32_e32 v219, v218, v219
	v_add_f32_e32 v220, v219, v220
	v_add_f32_e32 v221, v220, v221
	v_add_f32_e32 v222, v221, v222
	v_add_f32_e32 v223, v222, v223
	v_add_f32_e32 v224, v223, v224
	v_add_f32_e32 v225, v224, v225
	v_add_f32_e32 v226, v225, v226
	v_add_f32_e32 v227, v226, v227
	v_mov_b32_e32 v27, v227
	ds_write2st64_b32 v26, v212, v213 offset0:32 offset1:33
	ds_write2st64_b32 v26, v214, v215 offset0:34 offset1:35
	ds_write2st64_b32 v26, v216, v217 offset0:36 offset1:37
	ds_write2st64_b32 v26, v218, v219 offset0:38 offset1:39
	ds_write2st64_b32 v26, v220, v221 offset0:40 offset1:41
	ds_write2st64_b32 v26, v222, v223 offset0:42 offset1:43
	ds_write2st64_b32 v26, v224, v225 offset0:44 offset1:45
	ds_write2st64_b32 v26, v226, v227 offset0:46 offset1:47
	s_waitcnt lgkmcnt(8)
	v_add_f32_e32 v228, v27, v228
	v_add_f32_e32 v229, v228, v229
	v_add_f32_e32 v230, v229, v230
	v_add_f32_e32 v231, v230, v231
	v_add_f32_e32 v232, v231, v232
	v_add_f32_e32 v233, v232, v233
	v_add_f32_e32 v234, v233, v234
	v_add_f32_e32 v235, v234, v235
	v_add_f32_e32 v236, v235, v236
	v_add_f32_e32 v237, v236, v237
	v_add_f32_e32 v238, v237, v238
	v_add_f32_e32 v239, v238, v239
	v_add_f32_e32 v240, v239, v240
	v_add_f32_e32 v241, v240, v241
	v_add_f32_e32 v242, v241, v242
	v_add_f32_e32 v243, v242, v243
	v_mov_b32_e32 v27, v243
	ds_write2st64_b32 v26, v228, v229 offset0:48 offset1:49
	ds_write2st64_b32 v26, v230, v231 offset0:50 offset1:51
	ds_write2st64_b32 v26, v232, v233 offset0:52 offset1:53
	ds_write2st64_b32 v26, v234, v235 offset0:54 offset1:55
	ds_write2st64_b32 v26, v236, v237 offset0:56 offset1:57
	ds_write2st64_b32 v26, v238, v239 offset0:58 offset1:59
	ds_write2st64_b32 v26, v240, v241 offset0:60 offset1:61
	ds_write2st64_b32 v26, v242, v243 offset0:62 offset1:63
; __device__ __forceinline__ float blo(unsigned u) { return __uint_as_float(u << 16); }
; __device__ __forceinline__ float bhi(unsigned u) { return __uint_as_float(u & 0xffff0000u); }
; __device__ __forceinline__ void ph_r7_ca(const P& p, int j, int win, char* smem) {
;     ...
;       const int tau = tid >> 3, sc = tid & 7, col = h * 64 + sc * 8; const int row = rowmap(d, b, 64 * c + tau);
;       const bfr* rp = RK + (size_t)row * 4096 + col; uint4 pr = *(const uint4*)rp, pk = *(const uint4*)(rp + 1024);
;       unsigned ur[4] = {pr.x, pr.y, pr.z, pr.w}, uk[4] = {pk.x, pk.y, pk.z, pk.w};
;       float r8[8], k8[8], kr[8];
; #pragma unroll
;       for (int e = 0; e < 4; e++) { r8[2 * e] = blo(ur[e]); r8[2 * e + 1] = bhi(ur[e]); k8[2 * e] = blo(uk[e]); k8[2 * e + 1] = bhi(uk[e]); }
;       float ss = 0.f;
; #pragma unroll
;       for (int e = 0; e < 8; e++) { kr[e] = k8[e] * kkp[col + e]; ss += kr[e] * kr[e]; }
;       ss += __shfl_xor(ss, 1); ss += __shfl_xor(ss, 2); ss += __shfl_xor(ss, 4);
;       const float inv = __builtin_amdgcn_rsqf(fmaxf(ss, 1e-24f));
;       float bon = 0.f, o0[8], o1[8], o2[8], o3[8], o4[8], o5[8];
; #pragma unroll
;       for (int e = 0; e < 8; e++) {
;         const float cw = LW[tau * 64 + sc * 8 + e], cwm = tau > 0 ? LW[(tau - 1) * 64 + sc * 8 + e] : 0.f, cwl = LW[63 * 64 + sc * 8 + e], a = AT[tau * 64 + sc * 8 + e];
;         const float ka = kr[e] * inv, be = a * ka, kd = k8[e] * (1.f + (a - 1.f) * kap[col + e]); bon += r8[e] * kd * rkp[col + e];
;         const float e2 = __expf(-cw), e4 = __expf(cwl - cw);
;         o0[e] = ka * __expf(cwm); o1[e] = be * e2; o2[e] = kd * e2; o3[e] = r8[e] * __expf(cw); o4[e] = be * e4; o5[e] = kd * e4;
;         if (tau == 63) WL[sc * 8 + e] = __expf(cwl);
;       }
;       bon += __shfl_xor(bon, 1); bon += __shfl_xor(bon, 2); bon += __shfl_xor(bon, 4);
;       if (sc == 0) BON[((size_t)d * R_ + row) * 16 + h] = bon;
.LBB0_190:
	s_or_b64 exec, exec, s[30:31]
	s_waitcnt lgkmcnt(0)
	s_barrier
	s_waitcnt vmcnt(0)
	v_lshlrev_b32_e32 v213, 16, v8
	v_and_b32_e32 v51, 0xffff0000, v8
	v_lshlrev_b32_e32 v49, 16, v9
	v_and_b32_e32 v48, 0xffff0000, v9
	v_lshlrev_b32_e32 v47, 16, v10
	v_and_b32_e32 v46, 0xffff0000, v10
	v_lshlrev_b32_e32 v45, 16, v11
	v_and_b32_e32 v43, 0xffff0000, v11
	v_mul_f32_e32 v28, v244, v47
	v_mul_f32_e32 v12, v15, v51
	v_mul_f32_e32 v14, v14, v213
	v_mul_f32_e32 v13, v12, v12
	v_fmac_f32_e32 v13, v14, v14
	v_mul_f32_e32 v22, v16, v49
	v_fmac_f32_e32 v13, v22, v22
	v_mul_f32_e32 v19, v17, v48
	v_fmac_f32_e32 v13, v19, v19
	v_fmac_f32_e32 v13, v28, v28
	v_mul_f32_e32 v25, v245, v46
	v_fmac_f32_e32 v13, v25, v25
	v_mul_f32_e32 v215, v246, v45
	v_fmac_f32_e32 v13, v215, v215
	v_mul_f32_e32 v50, v247, v43
	v_fmac_f32_e32 v13, v50, v50
	global_load_dword v226, v0, s[96:97]
	global_load_dword v225, v0, s[48:49]
	v_lshl_add_u64 v[178:179], s[96:97], 0, v[0:1]
	v_lshl_add_u64 v[10:11], s[48:49], 0, v[0:1]
	global_load_dword v229, v[178:179], off offset:4
	global_load_dword v228, v[10:11], off offset:4
	global_load_dword v233, v[178:179], off offset:8
	global_load_dword v231, v[10:11], off offset:8
	global_load_dword v235, v[178:179], off offset:12
	global_load_dword v234, v[10:11], off offset:12
	global_load_dword v240, v[178:179], off offset:16
	global_load_dword v239, v[10:11], off offset:16
	global_load_dword v243, v[178:179], off offset:20
	global_load_dword v242, v[10:11], off offset:20
	global_load_dword v245, v[178:179], off offset:24
	global_load_dword v244, v[10:11], off offset:24
	global_load_dword v247, v[178:179], off offset:28
	global_load_dword v246, v[10:11], off offset:28
	v_add_f32_dpp v8, v13, v13 quad_perm:[1,0,3,2] row_mask:0xf bank_mask:0xf
	s_nop 1
	v_add_f32_dpp v219, v8, v8 quad_perm:[2,3,0,1] row_mask:0xf bank_mask:0xf
	s_nop 1
	v_mov_b32_dpp v220, v219 row_half_mirror row_mask:0xf bank_mask:0xf
	ds_read_b32 v13, v83 offset:64512
	ds_read_b32 v16, v83 offset:64516
	ds_read_b32 v23, v83 offset:64520
	ds_read_b32 v26, v83 offset:64524
	ds_read_b32 v212, v83 offset:64528
	ds_read_b32 v216, v83 offset:64532
	ds_read_b32 v224, v83 offset:64536
	ds_read_b32 v230, v83 offset:64540
	ds_read_b32 v15, v84 offset:16128
	ds_read_b32 v0, v87 offset:16128
	ds_read_b32 v24, v90 offset:16128
	ds_read_b32 v30, v93 offset:16128
	ds_read_b32 v214, v96 offset:16128
	ds_read_b32 v221, v99 offset:16128
	ds_read_b32 v227, v102 offset:16128
	ds_read_b32 v237, v105 offset:16128
	ds_read_b32 v21, v85
	ds_read_b32 v20, v88
	ds_read_b32 v41, v91
	ds_read_b32 v31, v94
	ds_read_b32 v223, v97
	ds_read_b32 v222, v100
	ds_read_b32 v241, v103
	ds_read_b32 v238, v106
	v_mov_b32_e32 v18, 0
	v_mov_b32_e32 v17, 0
	v_mov_b32_e32 v29, 0
	v_mov_b32_e32 v27, 0
	v_mov_b32_e32 v218, 0
	v_mov_b32_e32 v217, 0
	v_mov_b32_e32 v236, 0
	v_mov_b32_e32 v232, 0
	s_and_saveexec_b64 s[30:31], s[42:43]
	ds_read_b32 v18, v60 offset:64256
	ds_read_b32 v17, v60 offset:64260
	ds_read_b32 v29, v60 offset:64264
	ds_read_b32 v27, v60 offset:64268
	ds_read_b32 v218, v60 offset:64272
	ds_read_b32 v217, v60 offset:64276
	ds_read_b32 v236, v60 offset:64280
	ds_read_b32 v232, v60 offset:64284
	s_or_b64 exec, exec, s[30:31]
	s_waitcnt lgkmcnt(0)
	v_mul_f32_e32 v18, 0x3fb8aa3b, v18
	v_mul_f32_e32 v17, 0x3fb8aa3b, v17
	v_mul_f32_e32 v29, 0x3fb8aa3b, v29
	v_mul_f32_e32 v27, 0x3fb8aa3b, v27
	v_mul_f32_e32 v218, 0x3fb8aa3b, v218
	v_mul_f32_e32 v217, 0x3fb8aa3b, v217
	v_mul_f32_e32 v236, 0x3fb8aa3b, v236
	v_mul_f32_e32 v232, 0x3fb8aa3b, v232
	s_and_saveexec_b64 s[30:31], s[44:45]
	s_cbranch_execz .LBB0_222
	v_mul_f32_e32 v8, 0x3fb8aa3b, v15
	v_mul_f32_e32 v9, 0x3fb8aa3b, v0
	v_mul_f32_e32 v10, 0x3fb8aa3b, v24
	v_mul_f32_e32 v11, 0x3fb8aa3b, v30
	v_exp_f32_e32 v8, v8
	v_exp_f32_e32 v9, v9
	v_exp_f32_e32 v10, v10
	v_exp_f32_e32 v11, v11
	s_nop 0
	ds_write_b32 v86, v8
	ds_write_b32 v89, v9
	ds_write_b32 v92, v10
	ds_write_b32 v95, v11
	v_mul_f32_e32 v8, 0x3fb8aa3b, v214
	v_mul_f32_e32 v9, 0x3fb8aa3b, v221
	v_mul_f32_e32 v10, 0x3fb8aa3b, v227
	v_mul_f32_e32 v11, 0x3fb8aa3b, v237
	v_exp_f32_e32 v8, v8
	v_exp_f32_e32 v9, v9
	v_exp_f32_e32 v10, v10
	v_exp_f32_e32 v11, v11
	s_nop 0
	ds_write_b32 v98, v8
	ds_write_b32 v101, v9
	ds_write_b32 v104, v10
	ds_write_b32 v107, v11
.LBB0_222:
	s_or_b64 exec, exec, s[30:31]
	s_waitcnt lgkmcnt(14)
	v_add_f32_e32 v8, -1.0, v21
	s_waitcnt vmcnt(15)
	v_fma_f32 v8, v8, v226, 1.0
	v_lshlrev_b32_e32 v11, 16, v2
	v_mul_f32_e32 v8, v8, v213
	v_mul_f32_e32 v9, v8, v11
	s_waitcnt vmcnt(14)
	v_fma_f32 v178, v225, v9, 0
	v_and_b32_e32 v9, 0xffff0000, v2
	v_add_f32_e32 v2, -1.0, v20
	s_waitcnt vmcnt(13)
	v_fma_f32 v2, v2, v229, 1.0
	v_mul_f32_e32 v10, v2, v51
	v_mul_f32_e32 v2, v10, v9
	s_waitcnt vmcnt(12)
	v_fmac_f32_e32 v178, v228, v2
	v_add_f32_e32 v2, -1.0, v41
	s_waitcnt vmcnt(11)
	v_fma_f32 v2, v2, v233, 1.0
	v_lshlrev_b32_e32 v51, 16, v3
	v_mul_f32_e32 v49, v2, v49
	v_mul_f32_e32 v2, v49, v51
	s_waitcnt vmcnt(10)
	v_fmac_f32_e32 v178, v231, v2
	s_waitcnt lgkmcnt(12)
	v_add_f32_e32 v2, -1.0, v31
	s_waitcnt vmcnt(9)
	v_fma_f32 v2, v2, v235, 1.0
	v_and_b32_e32 v3, 0xffff0000, v3
	v_mul_f32_e32 v48, v2, v48
	v_mul_f32_e32 v2, v48, v3
	s_waitcnt vmcnt(8)
	v_fmac_f32_e32 v178, v234, v2
	s_waitcnt lgkmcnt(9)
	v_add_f32_e32 v2, -1.0, v223
	s_waitcnt vmcnt(7)
	v_fma_f32 v2, v2, v240, 1.0
	v_lshlrev_b32_e32 v213, 16, v4
	v_mul_f32_e32 v47, v2, v47
	v_mul_f32_e32 v2, v47, v213
	s_waitcnt vmcnt(6)
	v_fmac_f32_e32 v178, v239, v2
	s_waitcnt lgkmcnt(6)
	v_add_f32_e32 v2, -1.0, v222
	s_waitcnt vmcnt(5)
	v_fma_f32 v2, v2, v243, 1.0
	v_and_b32_e32 v4, 0xffff0000, v4
	v_mul_f32_e32 v46, v2, v46
	v_mul_f32_e32 v2, v46, v4
	s_waitcnt vmcnt(4)
	v_fmac_f32_e32 v178, v242, v2
	s_waitcnt lgkmcnt(3)
	v_add_f32_e32 v2, -1.0, v241
	s_waitcnt vmcnt(3)
	v_fma_f32 v2, v2, v245, 1.0
	v_lshlrev_b32_e32 v225, 16, v5
	v_mul_f32_e32 v45, v2, v45
	v_mul_f32_e32 v2, v45, v225
	s_waitcnt vmcnt(2)
	v_fmac_f32_e32 v178, v244, v2
	s_waitcnt lgkmcnt(0)
	v_add_f32_e32 v2, -1.0, v238
	s_waitcnt vmcnt(1)
	v_fma_f32 v2, v2, v247, 1.0
	v_and_b32_e32 v5, 0xffff0000, v5
	v_mul_f32_e32 v43, v2, v43
	v_mul_f32_e32 v2, v43, v5
	s_waitcnt vmcnt(0)
	v_fmac_f32_e32 v178, v246, v2
	s_nop 1
	v_add_f32_dpp v2, v178, v178 quad_perm:[1,0,3,2] row_mask:0xf bank_mask:0xf
	s_nop 1
	v_add_f32_dpp v2, v2, v2 quad_perm:[2,3,0,1] row_mask:0xf bank_mask:0xf
	s_nop 1
	v_mov_b32_dpp v226, v2 row_half_mirror row_mask:0xf bank_mask:0xf
	s_and_saveexec_b64 s[30:31], s[46:47]
	s_cbranch_execz .LBB0_224
	s_mul_i32 s28, s86, 0x8200
	v_lshl_add_u64 v[6:7], v[6:7], 0, s[28:29]
	v_readlane_b32 s40, v251, 15
	v_lshlrev_b64 v[6:7], 6, v[6:7]
	v_readlane_b32 s41, v251, 16
	s_lshl_b32 s28, s85, 2
	v_add_f32_e32 v2, v2, v226
	v_lshl_add_u64 v[6:7], s[40:41], 0, v[6:7]
	v_lshl_add_u64 v[6:7], v[6:7], 0, s[28:29]
	global_store_dword v[6:7], v2, off

; __device__ __forceinline__ void ph_ml_scan(const P& p, int j, char* smem0) {
;     ...
;       if (w == 0) {
;         int rho = d ? 63 - lane : lane;
;         float gi = pgi + gbias[(d * 2 + 0) * 8 + hh], gf = pgf + gbias[(d * 2 + 1) * 8 + hh];
;         float fc = fminf(gf, 0.f) - __logf(1.f + __expf(-fabsf(gf)));
;         const float bc = wscan_add(fc);
;         const float e = gi - bc, pm = wscan_max(e);
;         const float pml = __int_as_float(__builtin_amdgcn_readlane(__float_as_int(pm), 63)), bcl = __int_as_float(__builtin_amdgcn_readlane(__float_as_int(bc), 63));
;         const float mx_ = fmaxf(mcur, pml);
;         sEs[rho] = __expf(fminf(e, 80.f)); sCt[rho] = -fmaxf(mcur, pm); sBc[rho] = bc; sWg[rho] = __expf(e - mx_);
;         if (lane == 0) { sMisc[0] = mcur; sMisc[1] = __expf(mcur - mx_); }
;         mcur = bcl + mx_;
.LBB0_1161:
	v_mov_b32_e32 v54, s97
	s_and_saveexec_b64 s[10:11], s[42:43]
	s_cmp_gt_u32 s96, 3
	s_movk_i32 s9, 0x41ff
	s_cselect_b32 s9, s9, 0xff
	s_lshl_b32 s30, s96, 6
	s_sub_i32 s30, s93, s30
	s_add_i32 s9, s30, s9
	v_mov_b32_e32 v54, s9
	s_or_b64 exec, exec, s[10:11]
	s_waitcnt vmcnt(1)
	s_and_saveexec_b64 s[10:11], s[44:45]
	s_cbranch_execz .LBB0_1169
	s_mov_b32 s9, 0xbfb8aa3b
	v_mov_b32_e32 v57, v1
	v_mov_b32_e32 v58, v1
	v_mov_b32_e32 v59, 0xff61b1e6
	v_mov_b32_e32 v60, 0xff61b1e6
	v_mov_b32_e32 v61, 0xff61b1e6
	v_mov_b32_e32 v62, 0xff61b1e6
	v_mov_b32_e32 v64, 0xff61b1e6
	v_mov_b32_e32 v65, 0xff61b1e6
	v_max_f32_e32 v66, v104, v104
	v_add_f32_e32 v55, v99, v201
	v_mul_f32_e64 v63, |v55|, s9
	v_exp_f32_e32 v63, v63
	s_mov_b32 s9, 0x800000
	v_min_f32_e32 v55, 0, v55
	v_add_f32_e32 v56, v101, v202
	v_add_f32_e32 v63, 1.0, v63
	v_cmp_gt_f32_e32 vcc, s9, v63
	s_mov_b32 s9, 0x3f317217
	s_nop 0
	v_cndmask_b32_e64 v67, 0, 32, vcc
	v_ldexp_f32 v63, v63, v67
	v_log_f32_e32 v63, v63
	v_cndmask_b32_e32 v67, 0, v182, vcc
	v_mul_f32_e32 v68, 0x3f317217, v63
	v_fma_f32 v68, v63, s9, -v68
	v_fmac_f32_e32 v68, 0x3377d1cf, v63
	s_mov_b32 s9, 0x7f800000
	v_fmac_f32_e32 v68, 0x3f317217, v63
	v_cmp_lt_f32_e64 vcc, |v63|, s9
	s_nop 1
	v_cndmask_b32_e32 v63, v63, v68, vcc
	v_sub_f32_e32 v63, v63, v67
	v_sub_f32_e32 v55, v55, v63
	s_nop 1
	v_add_f32_dpp v55, v55, v55 row_shr:1 row_mask:0xf bank_mask:0xf bound_ctrl:1
	s_nop 1
	v_add_f32_dpp v55, v55, v55 row_shr:2 row_mask:0xf bank_mask:0xf bound_ctrl:1
	s_nop 1
	v_add_f32_dpp v55, v55, v55 row_shr:4 row_mask:0xf bank_mask:0xf bound_ctrl:1
	s_nop 1
	v_add_f32_dpp v55, v55, v55 row_shr:8 row_mask:0xf bank_mask:0xf bound_ctrl:1
	s_nop 1
	v_mov_b32_dpp v57, v55 row_bcast:15 row_mask:0xa bank_mask:0xf
	v_add_f32_e32 v55, v55, v57
	s_nop 1
	v_mov_b32_dpp v58, v55 row_bcast:31 row_mask:0xc bank_mask:0xf
	v_add_f32_e32 v57, v55, v58
	v_sub_f32_e32 v56, v56, v57
	v_min_f32_e32 v55, 0x42a00000, v56
	v_mul_f32_e32 v55, 0x3fb8aa3b, v55
	v_mov_b32_dpp v59, v56 row_shr:1 row_mask:0xf bank_mask:0xf
	v_max_f32_e32 v58, v59, v59
	v_max_f32_e32 v58, v56, v58
	v_exp_f32_e32 v59, v55
	v_readlane_b32 s9, v57, 63
	v_mov_b32_dpp v60, v58 row_shr:2 row_mask:0xf bank_mask:0xf
	v_max_f32_e32 v55, v60, v60
	v_max_f32_e32 v55, v58, v55
	v_max_f32_e64 v60, -v104, -v104
	s_nop 0
	v_mov_b32_dpp v61, v55 row_shr:4 row_mask:0xf bank_mask:0xf
	v_max_f32_e32 v58, v61, v61
	v_max_f32_e32 v55, v55, v58
	s_nop 1
	v_mov_b32_dpp v62, v55 row_shr:8 row_mask:0xf bank_mask:0xf
	v_max_f32_e32 v58, v62, v62
	v_max_f32_e32 v55, v55, v58
	s_nop 1
	v_mov_b32_dpp v64, v55 row_bcast:15 row_mask:0xa bank_mask:0xf
	v_max_f32_e32 v58, v64, v64
	v_max_f32_e32 v55, v55, v58
	s_nop 1
	v_mov_b32_dpp v65, v55 row_bcast:31 row_mask:0xc bank_mask:0xf
	v_max_f32_e32 v58, v65, v65
	v_max_f32_e32 v58, v55, v58
	s_nop 0
	v_readlane_b32 s30, v58, 63
	v_xor_b32_e32 v58, 0x80000000, v58
	v_min_f32_e32 v58, v60, v58
	v_max_f32_e64 v55, s30, s30
	v_max_f32_e32 v55, v66, v55
	v_sub_f32_e32 v56, v56, v55
	v_mul_f32_e32 v56, 0x3fb8aa3b, v56
	v_exp_f32_e32 v56, v56
	ds_write2st64_b32 v166, v59, v58 offset0:164 offset1:165
	ds_write2st64_b32 v166, v57, v56 offset0:166 offset1:167
	s_and_saveexec_b64 s[30:31], s[56:57]
	s_cbranch_execz .LBB0_1168
	v_sub_f32_e32 v56, v104, v55
	v_mul_f32_e32 v56, 0x3fb8aa3b, v56
	v_exp_f32_e32 v105, v56
	ds_write_b64 v91, v[104:105] offset:44288

; #define ML_ROW0(s_) (d == 0 ? b * BT_ + 64 * (s_) : rowmap(1, b, 64 * (s_) + 63))
; #define ML_ISSUE(s_) { const int r0n = ML_ROW0(s_); ML_LD(0, pq0, pk0) ML_LD(1, pq1, pk1) ML_LD(2, pq2, pk2) ML_LD(3, pq3, pk3) \
;       if (tid < 128) pv = *(const uint4*)(QKV + (size_t)(r0n + (tid >> 1)) * 4096 + 2048 + hh * 256 + sl * 16 + (tid & 1) * 8); \
;       if (w == 0) { const float* gp_ = GT + (size_t)(r0n + (d ? 63 - lane : lane)) * 32 + d * 16 + hh; pgi = gp_[0]; pgf = gp_[8]; } }
; __device__ __forceinline__ void ph_ml_scan(const P& p, int j, char* smem0) {
;     ...
;     ML_ISSUE(0)
;     __syncthreads();
;     for (int s = 0; s < NCH_; s++) {
;       const int r0 = ML_ROW0(s);
;       ML_COMMIT()
.LBB0_1169:
	s_or_b64 exec, exec, s[10:11]
	s_waitcnt vmcnt(8)
	ds_write_b128 v93, v[10:13]
	s_waitcnt vmcnt(7)
	ds_write_b128 v93, v[14:17] offset:17408
	s_waitcnt vmcnt(6)
	ds_write_b128 v155, v[18:21]
	s_waitcnt vmcnt(5)
	ds_write_b128 v155, v[22:25] offset:17408
	s_waitcnt vmcnt(4)
	ds_write_b128 v156, v[30:33]
	s_waitcnt vmcnt(3)
	ds_write_b128 v156, v[34:37] offset:17408
	s_waitcnt vmcnt(2)
	ds_write_b128 v157, v[38:41]
	s_waitcnt vmcnt(1)
	ds_write_b128 v157, v[42:45] offset:17408
	s_and_saveexec_b64 s[10:11], s[40:41]
	s_cbranch_execz .LBB0_1165
	ds_write_b16 v165, v26 offset:34816
	ds_write_b16_d16_hi v165, v26 offset:34960
	ds_write_b16 v165, v27 offset:35104
	ds_write_b16_d16_hi v165, v27 offset:35248
	ds_write_b16 v165, v28 offset:35392
	ds_write_b16_d16_hi v165, v28 offset:35536
	ds_write_b16 v165, v29 offset:35680
	ds_write_b16_d16_hi v165, v29 offset:35824

; __device__ __forceinline__ void ph_ml_scan(const P& p, int j, char* smem0) {
;     ...
;       { const int vr = tid >> 4, sg = (tid & 15) * 4; const uint2 vv_ = *(const uint2*)(sVT + vr * VS + sg); const float4 wg4 = *(const float4*)(sWg + sg);
;         *(uint2*)(sVW + vr * VS + sg) = uint2{cvtpk(blo(vv_.x) * wg4.x, bhi(vv_.x) * wg4.y), cvtpk(blo(vv_.y) * wg4.z, bhi(vv_.y) * wg4.w)}; }
;       bf16x8 qf[4];
; #pragma unroll
;       for (int ks = 0; ks < 4; ks++) qf[ks] = *(const bf16x8*)(sQ + (16 * w + l15) * QS + ks * 32 + q4 * 8);
;       f32x4 sacc[4];
; #pragma unroll
;       for (int a = 0; a < 4; a++) { sacc[a] = f32x4{0.f, 0.f, 0.f, 0.f};
; #pragma unroll
;         for (int ks = 0; ks < 4; ks++) { bf16x8 kf = *(const bf16x8*)(sK + (16 * a + l15) * QS + ks * 32 + q4 * 8); sacc[a] = __builtin_amdgcn_mfma_f32_16x16x32_bf16(kf, qf[ks], sacc[a], 0, 0, 0); } }
;       const float ctt = sCt[rt]; const float ect = __expf(ctt); float densum = 0.f;
; #pragma unroll
;       for (int a = 0; a < 4; a++) { const float4 ex4 = *(const float4*)(sEs + 16 * a + 4 * q4); const float exv[4] = {ex4.x, ex4.y, ex4.z, ex4.w};
; #pragma unroll
;         for (int jj = 0; jj < 4; jj++) { int rs_ = 16 * a + 4 * q4 + jj; bool valid = d == 0 ? rs_ <= rt : rs_ >= rt;
;           float wv = valid ? ect * exv[jj] : 0.f; sacc[a][jj] = sacc[a][jj] * wv; } }
;       bf16x8 sf[2], vf[2];
; #pragma unroll
;       for (int ks = 0; ks < 2; ks++) {
; #pragma unroll
;         for (int jj = 0; jj < 4; jj++) { sf[ks][jj] = (short)f2b(sacc[2 * ks][jj]); sf[ks][4 + jj] = (short)f2b(sacc[2 * ks + 1][jj]); }
;         uint2 v0 = *(const uint2*)(sVT + l15 * VS + 32 * ks + 4 * q4), v1 = *(const uint2*)(sVT + l15 * VS + 32 * ks + 16 + 4 * q4);
;         uint4 vv = uint4{v0.x, v0.y, v1.x, v1.y}; vf[ks] = *(bf16x8*)&vv;
;       }
;       f32x4 num = f32x4{0.f, 0.f, 0.f, 0.f}, numC = f32x4{0.f, 0.f, 0.f, 0.f}, dacc = f32x4{0.f, 0.f, 0.f, 0.f};
;       { const short one_ = (l15 & 3) == 0 ? (short)0x3F80 : (short)0; const bf16x8 onesA = bf16x8{one_, one_, one_, one_, one_, one_, one_, one_};
; #pragma unroll
;         for (int ks = 0; ks < 2; ks++) dacc = __builtin_amdgcn_mfma_f32_16x16x32_bf16(onesA, sf[ks], dacc, 0, 0, 0); }
;       densum = dacc[0];
; #pragma unroll
;       for (int ks = 0; ks < 2; ks++) num = __builtin_amdgcn_mfma_f32_16x16x32_bf16(vf[ks], sf[ks], num, 0, 0, 0);
; #pragma unroll
.LBB0_1181:
	ds_read_b64 v[58:59], v159 offset:34816
	ds_read_b128 v[54:57], v160 offset:42752
	v_add_u32_e32 v60, v161, v162
	v_add_u32_e32 v249, 0x8800, v187
	ds_read_b128 v[66:69], v60
	ds_read_b128 v[62:65], v60 offset:64
	ds_read_b128 v[236:239], v60 offset:128
	ds_read_b128 v[240:243], v60 offset:192
	ds_read_b128 v[204:207], v191 offset:17408
	ds_read_b128 v[208:211], v191 offset:17472
	ds_read_b128 v[212:215], v191 offset:17536
	ds_read_b128 v[216:219], v191 offset:17600
	ds_read_b128 v[220:223], v191 offset:21760
	ds_read_b128 v[224:227], v191 offset:21824
	ds_read_b128 v[228:231], v191 offset:21888
	ds_read_b128 v[232:235], v191 offset:21952
	s_waitcnt lgkmcnt(12)
	v_lshlrev_b32_e32 v60, 16, v58
	v_and_b32_e32 v61, 0xffff0000, v58
	v_lshlrev_b32_e32 v58, 16, v59
	v_and_b32_e32 v59, 0xffff0000, v59
	v_pk_mul_f32 v[54:55], v[54:55], v[60:61]
	v_pk_mul_f32 v[56:57], v[56:57], v[58:59]
	v_cvt_pk_bf16_f32 v54, v54, v55
	v_cvt_pk_bf16_f32 v55, v56, v57
	ds_write_b64 v159, v[54:55] offset:44304
	s_waitcnt lgkmcnt(5)
	v_mfma_f32_16x16x32_bf16 v[70:73], v[204:207], v[66:69], 0
	v_mfma_f32_16x16x32_bf16 v[70:73], v[208:211], v[62:65], v[70:73]
	v_mfma_f32_16x16x32_bf16 v[70:73], v[212:215], v[236:239], v[70:73]
	v_mfma_f32_16x16x32_bf16 v[70:73], v[216:219], v[240:243], v[70:73]
	ds_read_b128 v[204:207], v191 offset:26112
	ds_read_b128 v[208:211], v191 offset:26176
	ds_read_b128 v[212:215], v191 offset:26240
	ds_read_b128 v[216:219], v191 offset:26304
	ds_read_b32 v103, v195 offset:42240
	ds_read_b128 v[120:123], v164 offset:41984
	ds_read_b128 v[124:127], v164 offset:42048
	ds_read_b128 v[244:247], v164 offset:42112
	ds_read_b128 v[86:89], v164 offset:42176
	s_waitcnt lgkmcnt(10)
	v_mfma_f32_16x16x32_bf16 v[78:81], v[220:223], v[66:69], 0
	v_mfma_f32_16x16x32_bf16 v[78:81], v[224:227], v[62:65], v[78:81]
	v_mfma_f32_16x16x32_bf16 v[78:81], v[228:231], v[236:239], v[78:81]
	v_mfma_f32_16x16x32_bf16 v[78:81], v[232:235], v[240:243], v[78:81]
	ds_read_b128 v[220:223], v191 offset:30464
	ds_read_b128 v[224:227], v191 offset:30528
	ds_read_b128 v[228:231], v191 offset:30592
	ds_read_b128 v[232:235], v191 offset:30656
	s_waitcnt lgkmcnt(9)
	v_mfma_f32_16x16x32_bf16 v[82:85], v[204:207], v[66:69], 0
	v_mfma_f32_16x16x32_bf16 v[82:85], v[208:211], v[62:65], v[82:85]
	v_mfma_f32_16x16x32_bf16 v[82:85], v[212:215], v[236:239], v[82:85]
	v_mfma_f32_16x16x32_bf16 v[82:85], v[216:219], v[240:243], v[82:85]
	ds_read_b32 v248, v195 offset:42496
	ds_read2_b64 v[54:57], v249 offset1:4
	ds_read2_b64 v[58:61], v249 offset0:8 offset1:12
	ds_read_b128 v[204:207], v192 offset:37120
	ds_read_b128 v[208:211], v192 offset:37184
	ds_read_b128 v[212:215], v192 offset:37248
	s_waitcnt lgkmcnt(6)
	v_mfma_f32_16x16x32_bf16 v[74:77], v[220:223], v[66:69], 0
	v_mfma_f32_16x16x32_bf16 v[74:77], v[224:227], v[62:65], v[74:77]
	v_mfma_f32_16x16x32_bf16 v[74:77], v[228:231], v[236:239], v[74:77]
	v_mfma_f32_16x16x32_bf16 v[74:77], v[232:235], v[240:243], v[74:77]
	ds_read_b128 v[216:219], v192 offset:37312
	ds_read_b128 v[220:223], v163 offset:44032
	ds_read_b128 v[224:227], v163 offset:44096
	ds_read_b128 v[228:231], v163 offset:44160
	ds_read_b128 v[232:235], v163 offset:44224
	v_mul_f32_e32 v128, 0x3fb8aa3b, v103
	v_exp_f32_e32 v129, v128
	v_add_f32_e32 v198, v114, v103
	v_mul_f32_e32 v198, 0x3fb8aa3b, v198
	v_exp_f32_e32 v198, v198
	v_mul_f32_e32 v128, v129, v120
	v_cndmask_b32_e64 v128, 0, v128, s[58:59]
	v_mul_f32_e32 v70, v70, v128
	v_mul_f32_e32 v249, v129, v121
	v_cndmask_b32_e64 v249, 0, v249, s[60:61]
	v_mul_f32_e32 v71, v71, v249
	v_mul_f32_e32 v128, v129, v122
	v_cndmask_b32_e64 v128, 0, v128, s[62:63]
	v_mul_f32_e32 v72, v72, v128
	v_mul_f32_e32 v249, v129, v123
	v_cndmask_b32_e64 v249, 0, v249, s[64:65]
	v_mul_f32_e32 v73, v73, v249
	v_mul_f32_e32 v128, v129, v124
	v_cndmask_b32_e64 v128, 0, v128, s[66:67]
	v_mul_f32_e32 v78, v78, v128
	v_mul_f32_e32 v249, v129, v125
	v_cndmask_b32_e64 v249, 0, v249, s[68:69]
	v_mul_f32_e32 v79, v79, v249
	v_mul_f32_e32 v128, v129, v126
	v_cndmask_b32_e64 v128, 0, v128, s[70:71]
	v_mul_f32_e32 v80, v80, v128
	v_mul_f32_e32 v249, v129, v127
	v_cndmask_b32_e64 v249, 0, v249, s[72:73]
	v_mul_f32_e32 v81, v81, v249
	v_mul_f32_e32 v128, v129, v244
	v_cndmask_b32_e64 v128, 0, v128, s[74:75]
	v_mul_f32_e32 v82, v82, v128
	v_mul_f32_e32 v249, v129, v245
	v_cndmask_b32_e64 v249, 0, v249, s[76:77]
	v_mul_f32_e32 v83, v83, v249
	v_mul_f32_e32 v128, v129, v246
	v_cndmask_b32_e64 v128, 0, v128, s[78:79]
	v_mul_f32_e32 v84, v84, v128
	v_mul_f32_e32 v249, v129, v247
	v_cndmask_b32_e64 v249, 0, v249, s[80:81]
	v_mul_f32_e32 v85, v85, v249
	v_mul_f32_e32 v128, v129, v86
	v_cndmask_b32_e64 v128, 0, v128, s[82:83]
	v_mul_f32_e32 v74, v74, v128
	v_mul_f32_e32 v249, v129, v87
	v_cndmask_b32_e64 v249, 0, v249, s[84:85]
	v_mul_f32_e32 v75, v75, v249
	v_mul_f32_e32 v128, v129, v88
	v_cndmask_b32_e64 v128, 0, v128, s[86:87]
	v_mul_f32_e32 v76, v76, v128
	v_mul_f32_e32 v249, v129, v89
	v_cndmask_b32_e64 v249, 0, v249, s[88:89]
	v_mul_f32_e32 v77, v77, v249
	v_cvt_pk_bf16_f32 v120, v70, v71
	v_cvt_pk_bf16_f32 v121, v72, v73
	v_cvt_pk_bf16_f32 v122, v78, v79
	v_cvt_pk_bf16_f32 v123, v80, v81
	v_cvt_pk_bf16_f32 v124, v82, v83
	v_cvt_pk_bf16_f32 v125, v84, v85
	v_cvt_pk_bf16_f32 v126, v74, v75
	v_cvt_pk_bf16_f32 v127, v76, v77
	s_waitcnt lgkmcnt(8)
	v_sub_f32_e32 v197, v103, v248
	v_mul_f32_e32 v197, 0x3fb8aa3b, v197
	v_mfma_f32_16x16x32_bf16 v[70:73], v[2:5], v[120:123], 0
	v_mfma_f32_16x16x32_bf16 v[78:81], v[54:57], v[120:123], 0
	v_mfma_f32_16x16x32_bf16 v[70:73], v[2:5], v[124:127], v[70:73]
	v_mfma_f32_16x16x32_bf16 v[78:81], v[58:61], v[124:127], v[78:81]
	v_exp_f32_e32 v197, v197
	s_waitcnt lgkmcnt(4)
	v_mfma_f32_16x16x32_bf16 v[82:85], v[204:207], v[66:69], 0
	v_mfma_f32_16x16x32_bf16 v[82:85], v[208:211], v[62:65], v[82:85]
	v_mfma_f32_16x16x32_bf16 v[82:85], v[212:215], v[236:239], v[82:85]
	v_mfma_f32_16x16x32_bf16 v[82:85], v[216:219], v[240:243], v[82:85]
	s_waitcnt lgkmcnt(0)
	v_mfma_f32_16x16x32_bf16 v[74:77], v[220:223], v[66:69], 0
	v_mfma_f32_16x16x32_bf16 v[74:77], v[224:227], v[62:65], v[74:77]
	v_mfma_f32_16x16x32_bf16 v[74:77], v[228:231], v[236:239], v[74:77]
	v_mfma_f32_16x16x32_bf16 v[74:77], v[232:235], v[240:243], v[74:77]
	s_nop 7
	s_nop 1
	v_fmac_f32_e32 v70, v198, v74
	s_nop 0
	v_max_f32_e64 v54, |v70|, v197
	v_rcp_f32_e32 v58, v54
	v_pk_fma_f32 v[54:55], v[198:199], v[82:83], v[78:79] op_sel_hi:[0,1,1]
	v_pk_fma_f32 v[56:57], v[198:199], v[84:85], v[80:81] op_sel_hi:[0,1,1]
	v_pk_mul_f32 v[54:55], v[54:55], v[58:59] op_sel_hi:[1,0]
	v_pk_mul_f32 v[56:57], v[56:57], v[58:59] op_sel_hi:[1,0]
	s_and_saveexec_b64 s[10:11], s[90:91]
	s_cbranch_execz .LBB0_1199
	s_waitcnt vmcnt(0)
	v_lshlrev_b32_e32 v58, 16, v118
	v_and_b32_e32 v59, 0xffff0000, v118
	v_lshlrev_b32_e32 v60, 16, v119
	v_and_b32_e32 v61, 0xffff0000, v119
	v_pk_add_f32 v[56:57], v[56:57], v[60:61]
	v_pk_add_f32 v[54:55], v[54:55], v[58:59]
